# hgrn pass C: 32 dead phi copies per chunk removed; wait-skip tests dropped from the non-peeled loop copies
# speedup vs baseline: 1.0051x; 1.0026x over previous
.LBB0_342:
	s_add_u32 s33, s44, 0xfff80080
	s_addc_u32 s43, s45, -1
	s_add_i32 s50, 0, 0x10000
	s_cmp_eq_u32 s35, 28
	s_cselect_b32 s49, s27, s43
	s_cselect_b32 s48, s28, s33
	v_add_u32_e32 v142, s50, v149
	s_cselect_b32 s47, s25, s34
	s_cselect_b32 s46, s29, s31
	s_add_i32 s33, 0, 0x14000
	ds_read_b128 v[154:157], v142
	ds_read_b128 v[168:171], v142 offset:1024
	ds_read_b128 v[172:175], v142 offset:2048
	ds_read_b128 v[176:179], v142 offset:3072
	v_add_u32_e32 v142, s33, v149
	ds_read_b128 v[180:183], v142
	ds_read_b128 v[184:187], v142 offset:1024
	ds_read_b128 v[188:191], v142 offset:2048
	ds_read_b128 v[192:195], v142 offset:3072
	s_add_i32 m0, s12, 0xc000
	ds_read_b128 v[196:199], v167
	ds_read_b128 v[200:203], v167 offset:1024
	ds_read_b128 v[204:207], v167 offset:2048
	ds_read_b128 v[208:211], v167 offset:3072
	ds_read_b128 v[212:215], v167 offset:4096
	ds_read_b128 v[216:219], v167 offset:5120
	ds_read_b128 v[220:223], v167 offset:6144
	ds_read_b128 v[224:227], v167 offset:7168
	global_load_lds_dwordx4 v140, s[44:45]
	s_add_i32 m0, s12, 0xe000
	s_nop 0
	global_load_lds_dwordx4 v138, s[44:45]
	s_waitcnt vmcnt(8)
	s_waitcnt lgkmcnt(0)
	s_barrier
	s_setprio 1
	s_waitcnt lgkmcnt(0)
	v_mfma_f32_16x16x32_bf16 v[128:131], v[154:157], v[196:199], v[128:131]
	v_mfma_f32_16x16x32_bf16 v[124:127], v[172:175], v[196:199], v[124:127]
	v_mfma_f32_16x16x32_bf16 v[116:119], v[154:157], v[204:207], v[116:119]
	v_mfma_f32_16x16x32_bf16 v[108:111], v[172:175], v[204:207], v[108:111]
	v_mfma_f32_16x16x32_bf16 v[100:103], v[154:157], v[212:215], v[100:103]
	v_mfma_f32_16x16x32_bf16 v[92:95], v[172:175], v[212:215], v[92:95]
	v_mfma_f32_16x16x32_bf16 v[84:87], v[154:157], v[220:223], v[84:87]
	v_mfma_f32_16x16x32_bf16 v[76:79], v[172:175], v[220:223], v[76:79]
	v_mfma_f32_16x16x32_bf16 v[128:131], v[168:171], v[200:203], v[128:131]
	v_mfma_f32_16x16x32_bf16 v[124:127], v[176:179], v[200:203], v[124:127]
	v_mfma_f32_16x16x32_bf16 v[116:119], v[168:171], v[208:211], v[116:119]
	v_mfma_f32_16x16x32_bf16 v[108:111], v[176:179], v[208:211], v[108:111]
	v_mfma_f32_16x16x32_bf16 v[100:103], v[168:171], v[216:219], v[100:103]
	v_mfma_f32_16x16x32_bf16 v[92:95], v[176:179], v[216:219], v[92:95]
	v_mfma_f32_16x16x32_bf16 v[84:87], v[168:171], v[224:227], v[84:87]
	v_mfma_f32_16x16x32_bf16 v[76:79], v[176:179], v[224:227], v[76:79]
	v_mfma_f32_16x16x32_bf16 v[120:123], v[180:183], v[196:199], v[120:123]
	v_mfma_f32_16x16x32_bf16 v[112:115], v[188:191], v[196:199], v[112:115]
	v_mfma_f32_16x16x32_bf16 v[104:107], v[180:183], v[204:207], v[104:107]
	v_mfma_f32_16x16x32_bf16 v[96:99], v[188:191], v[204:207], v[96:99]
	v_mfma_f32_16x16x32_bf16 v[88:91], v[180:183], v[212:215], v[88:91]
	v_mfma_f32_16x16x32_bf16 v[80:83], v[188:191], v[212:215], v[80:83]
	v_mfma_f32_16x16x32_bf16 v[72:75], v[180:183], v[220:223], v[72:75]
	v_mfma_f32_16x16x32_bf16 v[68:71], v[188:191], v[220:223], v[68:71]
	v_mfma_f32_16x16x32_bf16 v[120:123], v[184:187], v[200:203], v[120:123]
	v_mfma_f32_16x16x32_bf16 v[112:115], v[192:195], v[200:203], v[112:115]
	v_mfma_f32_16x16x32_bf16 v[104:107], v[184:187], v[208:211], v[104:107]
	v_mfma_f32_16x16x32_bf16 v[96:99], v[192:195], v[208:211], v[96:99]
	v_mfma_f32_16x16x32_bf16 v[88:91], v[184:187], v[216:219], v[88:91]
	v_mfma_f32_16x16x32_bf16 v[80:83], v[192:195], v[216:219], v[80:83]
	v_mfma_f32_16x16x32_bf16 v[72:75], v[184:187], v[224:227], v[72:75]
	v_mfma_f32_16x16x32_bf16 v[68:71], v[192:195], v[224:227], v[68:71]
	s_setprio 0
	s_barrier
	s_add_i32 s43, s50, s10
	s_mov_b32 m0, s43
	ds_read_b128 v[196:199], v167 offset:16384
	ds_read_b128 v[200:203], v167 offset:17408
	ds_read_b128 v[204:207], v167 offset:18432
	ds_read_b128 v[208:211], v167 offset:19456
	ds_read_b128 v[212:215], v167 offset:20480
	ds_read_b128 v[216:219], v167 offset:21504
	ds_read_b128 v[220:223], v167 offset:22528
	ds_read_b128 v[224:227], v167 offset:23552
	global_load_lds_dwordx4 v2, s[46:47]
	s_add_i32 m0, s43, 0x2000
	s_add_u32 s50, s46, 0x80000
	s_addc_u32 s51, s47, 0
	s_add_i32 s33, s33, s10
	global_load_lds_dwordx4 v0, s[46:47]
	s_mov_b32 m0, s33
	s_nop 0
	global_load_lds_dwordx4 v2, s[50:51]
	s_add_i32 m0, s33, 0x2000
	s_nop 0
	global_load_lds_dwordx4 v0, s[50:51]
	s_mov_b32 m0, s12
	s_nop 0
	global_load_lds_dwordx4 v134, s[48:49]
	s_mov_b32 m0, s13
	s_nop 0
	global_load_lds_dwordx4 v132, s[48:49]
	s_waitcnt vmcnt(8)
	s_waitcnt lgkmcnt(0)
	s_barrier
	s_setprio 1
	s_waitcnt lgkmcnt(0)
	v_mfma_f32_16x16x32_bf16 v[64:67], v[154:157], v[196:199], v[64:67]
	v_mfma_f32_16x16x32_bf16 v[60:63], v[172:175], v[196:199], v[60:63]
	v_mfma_f32_16x16x32_bf16 v[52:55], v[154:157], v[204:207], v[52:55]
	v_mfma_f32_16x16x32_bf16 v[44:47], v[172:175], v[204:207], v[44:47]
	v_mfma_f32_16x16x32_bf16 v[36:39], v[154:157], v[212:215], v[36:39]
	v_mfma_f32_16x16x32_bf16 v[28:31], v[172:175], v[212:215], v[28:31]
	v_mfma_f32_16x16x32_bf16 v[20:23], v[154:157], v[220:223], v[20:23]
	v_mfma_f32_16x16x32_bf16 v[12:15], v[172:175], v[220:223], v[12:15]
	v_mfma_f32_16x16x32_bf16 v[64:67], v[168:171], v[200:203], v[64:67]
	v_mfma_f32_16x16x32_bf16 v[60:63], v[176:179], v[200:203], v[60:63]
	v_mfma_f32_16x16x32_bf16 v[52:55], v[168:171], v[208:211], v[52:55]
	v_mfma_f32_16x16x32_bf16 v[44:47], v[176:179], v[208:211], v[44:47]
	v_mfma_f32_16x16x32_bf16 v[36:39], v[168:171], v[216:219], v[36:39]
	v_mfma_f32_16x16x32_bf16 v[28:31], v[176:179], v[216:219], v[28:31]
	v_mfma_f32_16x16x32_bf16 v[20:23], v[168:171], v[224:227], v[20:23]
	v_mfma_f32_16x16x32_bf16 v[12:15], v[176:179], v[224:227], v[12:15]
	v_mfma_f32_16x16x32_bf16 v[56:59], v[180:183], v[196:199], v[56:59]
	v_mfma_f32_16x16x32_bf16 v[48:51], v[188:191], v[196:199], v[48:51]
	v_mfma_f32_16x16x32_bf16 v[40:43], v[180:183], v[204:207], v[40:43]
	v_mfma_f32_16x16x32_bf16 v[32:35], v[188:191], v[204:207], v[32:35]
	v_mfma_f32_16x16x32_bf16 v[24:27], v[180:183], v[212:215], v[24:27]
	v_mfma_f32_16x16x32_bf16 v[16:19], v[188:191], v[212:215], v[16:19]
	v_mfma_f32_16x16x32_bf16 v[8:11], v[180:183], v[220:223], v[8:11]
	v_mfma_f32_16x16x32_bf16 v[4:7], v[188:191], v[220:223], v[4:7]
	v_mfma_f32_16x16x32_bf16 v[56:59], v[184:187], v[200:203], v[56:59]
	v_mfma_f32_16x16x32_bf16 v[48:51], v[192:195], v[200:203], v[48:51]
	v_mfma_f32_16x16x32_bf16 v[40:43], v[184:187], v[208:211], v[40:43]
	v_mfma_f32_16x16x32_bf16 v[32:35], v[192:195], v[208:211], v[32:35]
	v_mfma_f32_16x16x32_bf16 v[24:27], v[184:187], v[216:219], v[24:27]
	v_mfma_f32_16x16x32_bf16 v[16:19], v[192:195], v[216:219], v[16:19]
	v_mfma_f32_16x16x32_bf16 v[8:11], v[184:187], v[224:227], v[8:11]
	v_mfma_f32_16x16x32_bf16 v[4:7], v[192:195], v[224:227], v[4:7]
	s_setprio 0
	s_barrier
	s_add_i32 s33, 0, 0x18000
	v_add_u32_e32 v144, s33, v149
	s_add_i32 s43, 0, 0x1c000
	ds_read_b128 v[154:157], v144
	ds_read_b128 v[168:171], v144 offset:1024
	ds_read_b128 v[172:175], v144 offset:2048
	ds_read_b128 v[176:179], v144 offset:3072
	v_add_u32_e32 v144, s43, v149
	ds_read_b128 v[180:183], v144
	ds_read_b128 v[184:187], v144 offset:1024
	ds_read_b128 v[188:191], v144 offset:2048
	ds_read_b128 v[192:195], v144 offset:3072
	s_add_u32 s48, s48, 0x80000
	s_addc_u32 s49, s49, 0
	s_mov_b32 m0, s14
	ds_read_b128 v[196:199], v167 offset:32768
	ds_read_b128 v[200:203], v167 offset:33792
	ds_read_b128 v[204:207], v167 offset:34816
	ds_read_b128 v[208:211], v167 offset:35840
	ds_read_b128 v[212:215], v167 offset:36864
	ds_read_b128 v[216:219], v167 offset:37888
	ds_read_b128 v[220:223], v167 offset:38912
	ds_read_b128 v[224:227], v167 offset:39936
	global_load_lds_dwordx4 v134, s[48:49]
	s_mov_b32 m0, s15
	s_nop 0
	global_load_lds_dwordx4 v132, s[48:49]
	s_waitcnt vmcnt(8)
	s_waitcnt lgkmcnt(0)
	s_barrier
	s_setprio 1
	s_waitcnt lgkmcnt(0)
	v_mfma_f32_16x16x32_bf16 v[128:131], v[154:157], v[196:199], v[128:131]
	v_mfma_f32_16x16x32_bf16 v[124:127], v[172:175], v[196:199], v[124:127]
	v_mfma_f32_16x16x32_bf16 v[116:119], v[154:157], v[204:207], v[116:119]
	v_mfma_f32_16x16x32_bf16 v[108:111], v[172:175], v[204:207], v[108:111]
	v_mfma_f32_16x16x32_bf16 v[100:103], v[154:157], v[212:215], v[100:103]
	v_mfma_f32_16x16x32_bf16 v[92:95], v[172:175], v[212:215], v[92:95]
	v_mfma_f32_16x16x32_bf16 v[84:87], v[154:157], v[220:223], v[84:87]
	v_mfma_f32_16x16x32_bf16 v[76:79], v[172:175], v[220:223], v[76:79]
	v_mfma_f32_16x16x32_bf16 v[128:131], v[168:171], v[200:203], v[128:131]
	v_mfma_f32_16x16x32_bf16 v[124:127], v[176:179], v[200:203], v[124:127]
	v_mfma_f32_16x16x32_bf16 v[116:119], v[168:171], v[208:211], v[116:119]
	v_mfma_f32_16x16x32_bf16 v[108:111], v[176:179], v[208:211], v[108:111]
	v_mfma_f32_16x16x32_bf16 v[100:103], v[168:171], v[216:219], v[100:103]
	v_mfma_f32_16x16x32_bf16 v[92:95], v[176:179], v[216:219], v[92:95]
	v_mfma_f32_16x16x32_bf16 v[84:87], v[168:171], v[224:227], v[84:87]
	v_mfma_f32_16x16x32_bf16 v[76:79], v[176:179], v[224:227], v[76:79]
	v_mfma_f32_16x16x32_bf16 v[120:123], v[180:183], v[196:199], v[120:123]
	v_mfma_f32_16x16x32_bf16 v[112:115], v[188:191], v[196:199], v[112:115]
	v_mfma_f32_16x16x32_bf16 v[104:107], v[180:183], v[204:207], v[104:107]
	v_mfma_f32_16x16x32_bf16 v[96:99], v[188:191], v[204:207], v[96:99]
	v_mfma_f32_16x16x32_bf16 v[88:91], v[180:183], v[212:215], v[88:91]
	v_mfma_f32_16x16x32_bf16 v[80:83], v[188:191], v[212:215], v[80:83]
	v_mfma_f32_16x16x32_bf16 v[72:75], v[180:183], v[220:223], v[72:75]
	v_mfma_f32_16x16x32_bf16 v[68:71], v[188:191], v[220:223], v[68:71]
	v_mfma_f32_16x16x32_bf16 v[120:123], v[184:187], v[200:203], v[120:123]
	v_mfma_f32_16x16x32_bf16 v[112:115], v[192:195], v[200:203], v[112:115]
	v_mfma_f32_16x16x32_bf16 v[104:107], v[184:187], v[208:211], v[104:107]
	v_mfma_f32_16x16x32_bf16 v[96:99], v[192:195], v[208:211], v[96:99]
	v_mfma_f32_16x16x32_bf16 v[88:91], v[184:187], v[216:219], v[88:91]
	v_mfma_f32_16x16x32_bf16 v[80:83], v[192:195], v[216:219], v[80:83]
	v_mfma_f32_16x16x32_bf16 v[72:75], v[184:187], v[224:227], v[72:75]
	v_mfma_f32_16x16x32_bf16 v[68:71], v[192:195], v[224:227], v[68:71]
	s_setprio 0
	s_barrier
	s_add_i32 s33, s33, s10
	s_mov_b32 m0, s33
	ds_read_b128 v[196:199], v167 offset:49152
	ds_read_b128 v[200:203], v167 offset:50176
	ds_read_b128 v[204:207], v167 offset:51200
	ds_read_b128 v[208:211], v167 offset:52224
	ds_read_b128 v[212:215], v167 offset:53248
	ds_read_b128 v[216:219], v167 offset:54272
	ds_read_b128 v[220:223], v167 offset:55296
	ds_read_b128 v[224:227], v167 offset:56320
	s_add_u32 s100, s46, 0x80
	s_addc_u32 s101, s47, 0
	global_load_lds_dwordx4 v2, s[100:101]
	s_add_i32 m0, s33, 0x2000
	s_add_u32 s46, s46, 0x80080
	s_addc_u32 s47, s47, 0
	s_add_i32 s33, s43, s10
	s_add_u32 s100, s46, 0xfff80000
	s_addc_u32 s101, s47, -1
	global_load_lds_dwordx4 v0, s[100:101]
	s_mov_b32 m0, s33
	s_nop 0
	global_load_lds_dwordx4 v2, s[46:47]
	s_add_i32 m0, s33, 0x2000
	s_nop 0
	global_load_lds_dwordx4 v0, s[46:47]
	s_mov_b32 m0, s16
	s_nop 0
	s_add_u32 s100, s48, 0xfff80080
	s_addc_u32 s101, s49, -1
	global_load_lds_dwordx4 v134, s[100:101]
	s_mov_b32 m0, s17
	s_nop 0
	s_add_u32 s100, s48, 0xfff80080
	s_addc_u32 s101, s49, -1
	global_load_lds_dwordx4 v132, s[100:101]
	s_waitcnt vmcnt(8)
	s_waitcnt lgkmcnt(0)
	s_barrier
	s_setprio 1
	s_waitcnt lgkmcnt(0)
	v_mfma_f32_16x16x32_bf16 v[64:67], v[154:157], v[196:199], v[64:67]
	v_mfma_f32_16x16x32_bf16 v[60:63], v[172:175], v[196:199], v[60:63]
	v_mfma_f32_16x16x32_bf16 v[52:55], v[154:157], v[204:207], v[52:55]
	v_mfma_f32_16x16x32_bf16 v[44:47], v[172:175], v[204:207], v[44:47]
	v_mfma_f32_16x16x32_bf16 v[36:39], v[154:157], v[212:215], v[36:39]
	v_mfma_f32_16x16x32_bf16 v[28:31], v[172:175], v[212:215], v[28:31]
	v_mfma_f32_16x16x32_bf16 v[20:23], v[154:157], v[220:223], v[20:23]
	v_mfma_f32_16x16x32_bf16 v[12:15], v[172:175], v[220:223], v[12:15]
	v_mfma_f32_16x16x32_bf16 v[64:67], v[168:171], v[200:203], v[64:67]
	v_mfma_f32_16x16x32_bf16 v[60:63], v[176:179], v[200:203], v[60:63]
	v_mfma_f32_16x16x32_bf16 v[52:55], v[168:171], v[208:211], v[52:55]
	v_mfma_f32_16x16x32_bf16 v[44:47], v[176:179], v[208:211], v[44:47]
	v_mfma_f32_16x16x32_bf16 v[36:39], v[168:171], v[216:219], v[36:39]
	v_mfma_f32_16x16x32_bf16 v[28:31], v[176:179], v[216:219], v[28:31]
	v_mfma_f32_16x16x32_bf16 v[20:23], v[168:171], v[224:227], v[20:23]
	v_mfma_f32_16x16x32_bf16 v[12:15], v[176:179], v[224:227], v[12:15]
	v_mfma_f32_16x16x32_bf16 v[56:59], v[180:183], v[196:199], v[56:59]
	v_mfma_f32_16x16x32_bf16 v[48:51], v[188:191], v[196:199], v[48:51]
	v_mfma_f32_16x16x32_bf16 v[40:43], v[180:183], v[204:207], v[40:43]
	v_mfma_f32_16x16x32_bf16 v[32:35], v[188:191], v[204:207], v[32:35]
	v_mfma_f32_16x16x32_bf16 v[24:27], v[180:183], v[212:215], v[24:27]
	v_mfma_f32_16x16x32_bf16 v[16:19], v[188:191], v[212:215], v[16:19]
	v_mfma_f32_16x16x32_bf16 v[8:11], v[180:183], v[220:223], v[8:11]
	v_mfma_f32_16x16x32_bf16 v[4:7], v[188:191], v[220:223], v[4:7]
	v_mfma_f32_16x16x32_bf16 v[56:59], v[184:187], v[200:203], v[56:59]
	v_mfma_f32_16x16x32_bf16 v[48:51], v[192:195], v[200:203], v[48:51]
	v_mfma_f32_16x16x32_bf16 v[40:43], v[184:187], v[208:211], v[40:43]
	v_mfma_f32_16x16x32_bf16 v[32:35], v[192:195], v[208:211], v[32:35]
	v_mfma_f32_16x16x32_bf16 v[24:27], v[184:187], v[216:219], v[24:27]
	v_mfma_f32_16x16x32_bf16 v[16:19], v[192:195], v[216:219], v[16:19]
	v_mfma_f32_16x16x32_bf16 v[8:11], v[184:187], v[224:227], v[8:11]
	v_mfma_f32_16x16x32_bf16 v[4:7], v[192:195], v[224:227], v[4:7]
	s_setprio 0
	s_barrier
	s_add_i32 s35, s35, 2
	s_add_u32 s31, s31, 0x100
	s_addc_u32 s34, s34, 0
	s_add_u32 s44, s44, 0x100
	s_addc_u32 s45, s45, 0
	s_cmp_gt_u32 s35, 29
	s_cbranch_scc0 .LBB0_342
	s_and_b64 vcc, exec, s[22:23]
	s_cbranch_vccz .LBB0_345
	s_barrier

.LBB0_643:
	s_or_b64 exec, exec, s[54:55]
	s_cmpk_eq_i32 s91, 0x1c0
	s_waitcnt vmcnt(0)
	ds_write_b32 v134, v64
	s_cbranch_scc1 .LBB0_645
	s_add_i32 s4, s83, s91
	s_add_i32 s4, s4, 64
	s_mul_hi_i32 s5, s4, 0x3800
	s_mulk_i32 s4, 0x3800
	s_add_u32 s54, s89, s4
	s_addc_u32 s55, s90, s5
	global_load_ushort v168, v114, s[54:55]
	global_load_ushort v186, v116, s[54:55]
	s_add_u32 s4, s54, 0x3800
	global_load_ushort v187, v118, s[54:55]
	s_addc_u32 s5, s55, 0
	global_load_ushort v169, v114, s[4:5]
	global_load_ushort v188, v116, s[4:5]
	global_load_ushort v189, v118, s[4:5]
	s_add_u32 s4, s54, 0x7000
	s_addc_u32 s5, s55, 0
	global_load_ushort v170, v114, s[4:5]
	global_load_ushort v190, v116, s[4:5]
	global_load_ushort v191, v118, s[4:5]
	s_add_u32 s4, s54, 0xa800
	s_addc_u32 s5, s55, 0
	global_load_ushort v171, v114, s[4:5]
	global_load_ushort v192, v116, s[4:5]
	global_load_ushort v193, v118, s[4:5]
	s_add_u32 s4, s54, 0xe000
	s_addc_u32 s5, s55, 0
	global_load_ushort v172, v114, s[4:5]
	global_load_ushort v194, v116, s[4:5]
	global_load_ushort v195, v118, s[4:5]
	s_add_u32 s4, s54, 0x11800
	s_addc_u32 s5, s55, 0
	global_load_ushort v173, v114, s[4:5]
	global_load_ushort v196, v116, s[4:5]
	global_load_ushort v197, v118, s[4:5]
	s_add_u32 s4, s54, 0x15000
	s_addc_u32 s5, s55, 0
	global_load_ushort v174, v114, s[4:5]
	global_load_ushort v198, v116, s[4:5]
	global_load_ushort v199, v118, s[4:5]
	s_add_u32 s4, s54, 0x18800
	s_addc_u32 s5, s55, 0
	global_load_ushort v175, v114, s[4:5]
	global_load_ushort v200, v116, s[4:5]
	global_load_ushort v201, v118, s[4:5]
	s_add_u32 s4, s54, 0x1c000
	s_addc_u32 s5, s55, 0
	global_load_ushort v178, v114, s[4:5]
	global_load_ushort v202, v116, s[4:5]
	global_load_ushort v203, v118, s[4:5]
	s_add_u32 s4, s54, 0x1f800
	s_addc_u32 s5, s55, 0
	global_load_ushort v179, v114, s[4:5]
	global_load_ushort v204, v116, s[4:5]
	global_load_ushort v205, v118, s[4:5]
	s_add_u32 s4, s54, 0x23000
	s_addc_u32 s5, s55, 0
	global_load_ushort v180, v114, s[4:5]
	global_load_ushort v206, v116, s[4:5]
	global_load_ushort v207, v118, s[4:5]
	s_add_u32 s4, s54, 0x26800
	s_addc_u32 s5, s55, 0
	global_load_ushort v181, v114, s[4:5]
	global_load_ushort v208, v116, s[4:5]
	global_load_ushort v209, v118, s[4:5]
	s_add_u32 s4, s54, 0x2a000
	s_addc_u32 s5, s55, 0
	global_load_ushort v182, v114, s[4:5]
	global_load_ushort v210, v116, s[4:5]
	global_load_ushort v211, v118, s[4:5]
	s_add_u32 s4, s54, 0x2d800
	s_addc_u32 s5, s55, 0
	global_load_ushort v183, v114, s[4:5]
	global_load_ushort v212, v116, s[4:5]
	global_load_ushort v213, v118, s[4:5]
	s_add_u32 s4, s54, 0x31000
	s_addc_u32 s5, s55, 0
	global_load_ushort v184, v114, s[4:5]
	global_load_ushort v214, v116, s[4:5]
	global_load_ushort v215, v118, s[4:5]
	s_add_u32 s4, s54, 0x34800
	s_addc_u32 s5, s55, 0
	global_load_ushort v185, v114, s[4:5]
	global_load_ushort v216, v116, s[4:5]
	global_load_ushort v217, v118, s[4:5]

.LBB0_1066:
	s_add_u32 s12, s44, 0xfff80080
	s_addc_u32 s13, s45, -1
	s_add_i32 s14, 0, 0x10000
	s_cmp_eq_u32 s11, 28
	s_cselect_b32 s49, s5, s13
	s_cselect_b32 s48, s6, s12
	s_cselect_b32 s47, s7, s10
	s_cselect_b32 s46, s8, s9
	s_add_i32 s15, 0, 0x14000
	v_add_u32_e32 v154, s14, v163
	v_add_u32_e32 v158, s15, v163
	ds_read_b128 v[142:145], v154
	ds_read_b128 v[146:149], v154 offset:1024
	ds_read_b128 v[150:153], v154 offset:2048
	ds_read_b128 v[154:157], v154 offset:3072
	ds_read_b128 v[168:171], v158
	ds_read_b128 v[172:175], v158 offset:1024
	ds_read_b128 v[176:179], v158 offset:2048
	ds_read_b128 v[180:183], v158 offset:3072
	s_add_i32 m0, s60, 0xc000
	ds_read_b128 v[184:187], v167
	ds_read_b128 v[188:191], v167 offset:1024
	ds_read_b128 v[192:195], v167 offset:2048
	ds_read_b128 v[196:199], v167 offset:3072
	ds_read_b128 v[200:203], v167 offset:4096
	ds_read_b128 v[204:207], v167 offset:5120
	ds_read_b128 v[208:211], v167 offset:6144
	ds_read_b128 v[212:215], v167 offset:7168
	global_load_lds_dwordx4 v140, s[44:45]
	s_add_i32 m0, s60, 0xe000
	s_nop 0
	global_load_lds_dwordx4 v138, s[44:45]
	s_waitcnt vmcnt(8)
	s_waitcnt lgkmcnt(0)
	s_barrier
	s_setprio 1
	s_waitcnt lgkmcnt(0)
	v_mfma_f32_16x16x32_bf16 v[124:127], v[142:145], v[184:187], v[124:127]
	v_mfma_f32_16x16x32_bf16 v[120:123], v[150:153], v[184:187], v[120:123]
	v_mfma_f32_16x16x32_bf16 v[112:115], v[142:145], v[192:195], v[112:115]
	v_mfma_f32_16x16x32_bf16 v[104:107], v[150:153], v[192:195], v[104:107]
	v_mfma_f32_16x16x32_bf16 v[96:99], v[142:145], v[200:203], v[96:99]
	v_mfma_f32_16x16x32_bf16 v[88:91], v[150:153], v[200:203], v[88:91]
	v_mfma_f32_16x16x32_bf16 v[80:83], v[142:145], v[208:211], v[80:83]
	v_mfma_f32_16x16x32_bf16 v[72:75], v[150:153], v[208:211], v[72:75]
	v_mfma_f32_16x16x32_bf16 v[124:127], v[146:149], v[188:191], v[124:127]
	v_mfma_f32_16x16x32_bf16 v[120:123], v[154:157], v[188:191], v[120:123]
	v_mfma_f32_16x16x32_bf16 v[112:115], v[146:149], v[196:199], v[112:115]
	v_mfma_f32_16x16x32_bf16 v[104:107], v[154:157], v[196:199], v[104:107]
	v_mfma_f32_16x16x32_bf16 v[96:99], v[146:149], v[204:207], v[96:99]
	v_mfma_f32_16x16x32_bf16 v[88:91], v[154:157], v[204:207], v[88:91]
	v_mfma_f32_16x16x32_bf16 v[80:83], v[146:149], v[212:215], v[80:83]
	v_mfma_f32_16x16x32_bf16 v[72:75], v[154:157], v[212:215], v[72:75]
	v_mfma_f32_16x16x32_bf16 v[128:131], v[168:171], v[184:187], v[128:131]
	v_mfma_f32_16x16x32_bf16 v[116:119], v[176:179], v[184:187], v[116:119]
	v_mfma_f32_16x16x32_bf16 v[108:111], v[168:171], v[192:195], v[108:111]
	v_mfma_f32_16x16x32_bf16 v[100:103], v[176:179], v[192:195], v[100:103]
	v_mfma_f32_16x16x32_bf16 v[92:95], v[168:171], v[200:203], v[92:95]
	v_mfma_f32_16x16x32_bf16 v[84:87], v[176:179], v[200:203], v[84:87]
	v_mfma_f32_16x16x32_bf16 v[76:79], v[168:171], v[208:211], v[76:79]
	v_mfma_f32_16x16x32_bf16 v[68:71], v[176:179], v[208:211], v[68:71]
	v_mfma_f32_16x16x32_bf16 v[128:131], v[172:175], v[188:191], v[128:131]
	v_mfma_f32_16x16x32_bf16 v[116:119], v[180:183], v[188:191], v[116:119]
	v_mfma_f32_16x16x32_bf16 v[108:111], v[172:175], v[196:199], v[108:111]
	v_mfma_f32_16x16x32_bf16 v[100:103], v[180:183], v[196:199], v[100:103]
	v_mfma_f32_16x16x32_bf16 v[92:95], v[172:175], v[204:207], v[92:95]
	v_mfma_f32_16x16x32_bf16 v[84:87], v[180:183], v[204:207], v[84:87]
	v_mfma_f32_16x16x32_bf16 v[76:79], v[172:175], v[212:215], v[76:79]
	v_mfma_f32_16x16x32_bf16 v[68:71], v[180:183], v[212:215], v[68:71]
	s_setprio 0
	s_barrier
	s_add_i32 s12, s14, s56
	s_mov_b32 m0, s12
	ds_read_b128 v[184:187], v167 offset:16384
	ds_read_b128 v[188:191], v167 offset:17408
	ds_read_b128 v[192:195], v167 offset:18432
	ds_read_b128 v[196:199], v167 offset:19456
	ds_read_b128 v[200:203], v167 offset:20480
	ds_read_b128 v[204:207], v167 offset:21504
	ds_read_b128 v[208:211], v167 offset:22528
	ds_read_b128 v[212:215], v167 offset:23552
	global_load_lds_dwordx4 v2, s[46:47]
	s_add_i32 m0, s12, 0x2000
	s_add_u32 s12, s46, 0x80000
	s_addc_u32 s13, s47, 0
	s_add_i32 s14, s15, s56
	global_load_lds_dwordx4 v0, s[46:47]
	s_mov_b32 m0, s14
	s_nop 0
	global_load_lds_dwordx4 v2, s[12:13]
	s_add_i32 m0, s14, 0x2000
	s_nop 0
	global_load_lds_dwordx4 v0, s[12:13]
	s_mov_b32 m0, s60
	s_nop 0
	global_load_lds_dwordx4 v134, s[48:49]
	s_mov_b32 m0, s61
	s_nop 0
	global_load_lds_dwordx4 v132, s[48:49]
	s_waitcnt vmcnt(8)
	s_waitcnt lgkmcnt(0)
	s_barrier
	s_setprio 1
	s_waitcnt lgkmcnt(0)
	v_mfma_f32_16x16x32_bf16 v[64:67], v[142:145], v[184:187], v[64:67]
	v_mfma_f32_16x16x32_bf16 v[56:59], v[150:153], v[184:187], v[56:59]
	v_mfma_f32_16x16x32_bf16 v[48:51], v[142:145], v[192:195], v[48:51]
	v_mfma_f32_16x16x32_bf16 v[40:43], v[150:153], v[192:195], v[40:43]
	v_mfma_f32_16x16x32_bf16 v[32:35], v[142:145], v[200:203], v[32:35]
	v_mfma_f32_16x16x32_bf16 v[24:27], v[150:153], v[200:203], v[24:27]
	v_mfma_f32_16x16x32_bf16 v[16:19], v[142:145], v[208:211], v[16:19]
	v_mfma_f32_16x16x32_bf16 v[8:11], v[150:153], v[208:211], v[8:11]
	v_mfma_f32_16x16x32_bf16 v[64:67], v[146:149], v[188:191], v[64:67]
	v_mfma_f32_16x16x32_bf16 v[56:59], v[154:157], v[188:191], v[56:59]
	v_mfma_f32_16x16x32_bf16 v[48:51], v[146:149], v[196:199], v[48:51]
	v_mfma_f32_16x16x32_bf16 v[40:43], v[154:157], v[196:199], v[40:43]
	v_mfma_f32_16x16x32_bf16 v[32:35], v[146:149], v[204:207], v[32:35]
	v_mfma_f32_16x16x32_bf16 v[24:27], v[154:157], v[204:207], v[24:27]
	v_mfma_f32_16x16x32_bf16 v[16:19], v[146:149], v[212:215], v[16:19]
	v_mfma_f32_16x16x32_bf16 v[8:11], v[154:157], v[212:215], v[8:11]
	v_mfma_f32_16x16x32_bf16 v[60:63], v[168:171], v[184:187], v[60:63]
	v_mfma_f32_16x16x32_bf16 v[52:55], v[176:179], v[184:187], v[52:55]
	v_mfma_f32_16x16x32_bf16 v[44:47], v[168:171], v[192:195], v[44:47]
	v_mfma_f32_16x16x32_bf16 v[36:39], v[176:179], v[192:195], v[36:39]
	v_mfma_f32_16x16x32_bf16 v[28:31], v[168:171], v[200:203], v[28:31]
	v_mfma_f32_16x16x32_bf16 v[20:23], v[176:179], v[200:203], v[20:23]
	v_mfma_f32_16x16x32_bf16 v[12:15], v[168:171], v[208:211], v[12:15]
	v_mfma_f32_16x16x32_bf16 v[4:7], v[176:179], v[208:211], v[4:7]
	v_mfma_f32_16x16x32_bf16 v[60:63], v[172:175], v[188:191], v[60:63]
	v_mfma_f32_16x16x32_bf16 v[52:55], v[180:183], v[188:191], v[52:55]
	v_mfma_f32_16x16x32_bf16 v[44:47], v[172:175], v[196:199], v[44:47]
	v_mfma_f32_16x16x32_bf16 v[36:39], v[180:183], v[196:199], v[36:39]
	v_mfma_f32_16x16x32_bf16 v[28:31], v[172:175], v[204:207], v[28:31]
	v_mfma_f32_16x16x32_bf16 v[20:23], v[180:183], v[204:207], v[20:23]
	v_mfma_f32_16x16x32_bf16 v[12:15], v[172:175], v[212:215], v[12:15]
	v_mfma_f32_16x16x32_bf16 v[4:7], v[180:183], v[212:215], v[4:7]
	s_setprio 0
	s_barrier
	s_add_i32 s14, 0, 0x18000
	s_add_i32 s15, 0, 0x1c000
	v_add_u32_e32 v154, s14, v163
	v_add_u32_e32 v160, s15, v163
	ds_read_b128 v[142:145], v154
	ds_read_b128 v[146:149], v154 offset:1024
	ds_read_b128 v[150:153], v154 offset:2048
	ds_read_b128 v[154:157], v154 offset:3072
	ds_read_b128 v[168:171], v160
	ds_read_b128 v[172:175], v160 offset:1024
	ds_read_b128 v[176:179], v160 offset:2048
	ds_read_b128 v[180:183], v160 offset:3072
	s_add_u32 s12, s48, 0x80000
	s_addc_u32 s13, s49, 0
	s_mov_b32 m0, s62
	ds_read_b128 v[184:187], v167 offset:32768
	ds_read_b128 v[188:191], v167 offset:33792
	ds_read_b128 v[192:195], v167 offset:34816
	ds_read_b128 v[196:199], v167 offset:35840
	ds_read_b128 v[200:203], v167 offset:36864
	ds_read_b128 v[204:207], v167 offset:37888
	ds_read_b128 v[208:211], v167 offset:38912
	ds_read_b128 v[212:215], v167 offset:39936
	global_load_lds_dwordx4 v134, s[12:13]
	s_mov_b32 m0, s63
	s_nop 0
	global_load_lds_dwordx4 v132, s[12:13]
	s_waitcnt vmcnt(8)
	s_waitcnt lgkmcnt(0)
	s_barrier
	s_setprio 1
	s_waitcnt lgkmcnt(0)
	v_mfma_f32_16x16x32_bf16 v[124:127], v[142:145], v[184:187], v[124:127]
	v_mfma_f32_16x16x32_bf16 v[120:123], v[150:153], v[184:187], v[120:123]
	v_mfma_f32_16x16x32_bf16 v[112:115], v[142:145], v[192:195], v[112:115]
	v_mfma_f32_16x16x32_bf16 v[104:107], v[150:153], v[192:195], v[104:107]
	v_mfma_f32_16x16x32_bf16 v[96:99], v[142:145], v[200:203], v[96:99]
	v_mfma_f32_16x16x32_bf16 v[88:91], v[150:153], v[200:203], v[88:91]
	v_mfma_f32_16x16x32_bf16 v[80:83], v[142:145], v[208:211], v[80:83]
	v_mfma_f32_16x16x32_bf16 v[72:75], v[150:153], v[208:211], v[72:75]
	v_mfma_f32_16x16x32_bf16 v[124:127], v[146:149], v[188:191], v[124:127]
	v_mfma_f32_16x16x32_bf16 v[120:123], v[154:157], v[188:191], v[120:123]
	v_mfma_f32_16x16x32_bf16 v[112:115], v[146:149], v[196:199], v[112:115]
	v_mfma_f32_16x16x32_bf16 v[104:107], v[154:157], v[196:199], v[104:107]
	v_mfma_f32_16x16x32_bf16 v[96:99], v[146:149], v[204:207], v[96:99]
	v_mfma_f32_16x16x32_bf16 v[88:91], v[154:157], v[204:207], v[88:91]
	v_mfma_f32_16x16x32_bf16 v[80:83], v[146:149], v[212:215], v[80:83]
	v_mfma_f32_16x16x32_bf16 v[72:75], v[154:157], v[212:215], v[72:75]
	v_mfma_f32_16x16x32_bf16 v[128:131], v[168:171], v[184:187], v[128:131]
	v_mfma_f32_16x16x32_bf16 v[116:119], v[176:179], v[184:187], v[116:119]
	v_mfma_f32_16x16x32_bf16 v[108:111], v[168:171], v[192:195], v[108:111]
	v_mfma_f32_16x16x32_bf16 v[100:103], v[176:179], v[192:195], v[100:103]
	v_mfma_f32_16x16x32_bf16 v[92:95], v[168:171], v[200:203], v[92:95]
	v_mfma_f32_16x16x32_bf16 v[84:87], v[176:179], v[200:203], v[84:87]
	v_mfma_f32_16x16x32_bf16 v[76:79], v[168:171], v[208:211], v[76:79]
	v_mfma_f32_16x16x32_bf16 v[68:71], v[176:179], v[208:211], v[68:71]
	v_mfma_f32_16x16x32_bf16 v[128:131], v[172:175], v[188:191], v[128:131]
	v_mfma_f32_16x16x32_bf16 v[116:119], v[180:183], v[188:191], v[116:119]
	v_mfma_f32_16x16x32_bf16 v[108:111], v[172:175], v[196:199], v[108:111]
	v_mfma_f32_16x16x32_bf16 v[100:103], v[180:183], v[196:199], v[100:103]
	v_mfma_f32_16x16x32_bf16 v[92:95], v[172:175], v[204:207], v[92:95]
	v_mfma_f32_16x16x32_bf16 v[84:87], v[180:183], v[204:207], v[84:87]
	v_mfma_f32_16x16x32_bf16 v[76:79], v[172:175], v[212:215], v[76:79]
	v_mfma_f32_16x16x32_bf16 v[68:71], v[180:183], v[212:215], v[68:71]
	s_setprio 0
	s_barrier
	s_add_i32 s12, s14, s56
	s_mov_b32 m0, s12
	ds_read_b128 v[184:187], v167 offset:49152
	ds_read_b128 v[188:191], v167 offset:50176
	ds_read_b128 v[192:195], v167 offset:51200
	ds_read_b128 v[196:199], v167 offset:52224
	ds_read_b128 v[200:203], v167 offset:53248
	ds_read_b128 v[204:207], v167 offset:54272
	ds_read_b128 v[208:211], v167 offset:55296
	ds_read_b128 v[212:215], v167 offset:56320
	s_add_u32 s100, s46, 0x80
	s_addc_u32 s101, s47, 0
	global_load_lds_dwordx4 v2, s[100:101]
	s_add_i32 m0, s12, 0x2000
	s_add_u32 s12, s46, 0x80080
	s_addc_u32 s13, s47, 0
	s_add_i32 s14, s15, s56
	s_add_u32 s100, s46, 0x80
	s_addc_u32 s101, s47, 0
	global_load_lds_dwordx4 v0, s[100:101]
	s_mov_b32 m0, s14
	s_nop 0
	global_load_lds_dwordx4 v2, s[12:13]
	s_add_i32 m0, s14, 0x2000
	s_nop 0
	global_load_lds_dwordx4 v0, s[12:13]
	s_mov_b32 m0, s64
	s_nop 0
	s_add_u32 s100, s48, 0x80
	s_addc_u32 s101, s49, 0
	global_load_lds_dwordx4 v134, s[100:101]
	s_mov_b32 m0, s65
	s_nop 0
	s_add_u32 s100, s48, 0x80
	s_addc_u32 s101, s49, 0
	global_load_lds_dwordx4 v132, s[100:101]
	s_waitcnt vmcnt(8)
	s_waitcnt lgkmcnt(0)
	s_barrier
	s_setprio 1
	s_waitcnt lgkmcnt(0)
	v_mfma_f32_16x16x32_bf16 v[64:67], v[142:145], v[184:187], v[64:67]
	v_mfma_f32_16x16x32_bf16 v[56:59], v[150:153], v[184:187], v[56:59]
	v_mfma_f32_16x16x32_bf16 v[48:51], v[142:145], v[192:195], v[48:51]
	v_mfma_f32_16x16x32_bf16 v[40:43], v[150:153], v[192:195], v[40:43]
	v_mfma_f32_16x16x32_bf16 v[32:35], v[142:145], v[200:203], v[32:35]
	v_mfma_f32_16x16x32_bf16 v[24:27], v[150:153], v[200:203], v[24:27]
	v_mfma_f32_16x16x32_bf16 v[16:19], v[142:145], v[208:211], v[16:19]
	v_mfma_f32_16x16x32_bf16 v[8:11], v[150:153], v[208:211], v[8:11]
	v_mfma_f32_16x16x32_bf16 v[64:67], v[146:149], v[188:191], v[64:67]
	v_mfma_f32_16x16x32_bf16 v[56:59], v[154:157], v[188:191], v[56:59]
	v_mfma_f32_16x16x32_bf16 v[48:51], v[146:149], v[196:199], v[48:51]
	v_mfma_f32_16x16x32_bf16 v[40:43], v[154:157], v[196:199], v[40:43]
	v_mfma_f32_16x16x32_bf16 v[32:35], v[146:149], v[204:207], v[32:35]
	v_mfma_f32_16x16x32_bf16 v[24:27], v[154:157], v[204:207], v[24:27]
	v_mfma_f32_16x16x32_bf16 v[16:19], v[146:149], v[212:215], v[16:19]
	v_mfma_f32_16x16x32_bf16 v[8:11], v[154:157], v[212:215], v[8:11]
	v_mfma_f32_16x16x32_bf16 v[60:63], v[168:171], v[184:187], v[60:63]
	v_mfma_f32_16x16x32_bf16 v[52:55], v[176:179], v[184:187], v[52:55]
	v_mfma_f32_16x16x32_bf16 v[44:47], v[168:171], v[192:195], v[44:47]
	v_mfma_f32_16x16x32_bf16 v[36:39], v[176:179], v[192:195], v[36:39]
	v_mfma_f32_16x16x32_bf16 v[28:31], v[168:171], v[200:203], v[28:31]
	v_mfma_f32_16x16x32_bf16 v[20:23], v[176:179], v[200:203], v[20:23]
	v_mfma_f32_16x16x32_bf16 v[12:15], v[168:171], v[208:211], v[12:15]
	v_mfma_f32_16x16x32_bf16 v[4:7], v[176:179], v[208:211], v[4:7]
	v_mfma_f32_16x16x32_bf16 v[60:63], v[172:175], v[188:191], v[60:63]
	v_mfma_f32_16x16x32_bf16 v[52:55], v[180:183], v[188:191], v[52:55]
	v_mfma_f32_16x16x32_bf16 v[44:47], v[172:175], v[196:199], v[44:47]
	v_mfma_f32_16x16x32_bf16 v[36:39], v[180:183], v[196:199], v[36:39]
	v_mfma_f32_16x16x32_bf16 v[28:31], v[172:175], v[204:207], v[28:31]
	v_mfma_f32_16x16x32_bf16 v[20:23], v[180:183], v[204:207], v[20:23]
	v_mfma_f32_16x16x32_bf16 v[12:15], v[172:175], v[212:215], v[12:15]
	v_mfma_f32_16x16x32_bf16 v[4:7], v[180:183], v[212:215], v[4:7]
	s_setprio 0
	s_barrier
	s_add_i32 s11, s11, 2
	s_add_u32 s9, s9, 0x100
	s_addc_u32 s10, s10, 0
	s_add_u32 s44, s44, 0x100
	s_addc_u32 s45, s45, 0
	s_cmp_gt_u32 s11, 29
	s_cbranch_scc0 .LBB0_1066
	s_and_b64 vcc, exec, s[22:23]
	s_cbranch_vccz .LBB0_1069
	s_barrier
